# v11: v8 plus GLA state scan (pass 2) loads issued up front instead of one dependent round trip per chunk; bit-identical arithmetic order
# baseline (speedup 1.0000x reference)
; DI int tidx() { int t = threadIdx.x; asm volatile("" : "+v"(t)); return t; }
; DI void gla_pass2(float* __restrict__ Ubuf, const float* __restrict__ Ebuf) {
;   const int idx = blockIdx.x * 256 + tidx();
;   if (idx < 32 * 64 * 32) {
;     const int bh = idx >> 11, d = (idx >> 5) & 63, v4 = idx & 31;
;     f32x4 S = (f32x4){0.f, 0.f, 0.f, 0.f};
; #pragma unroll 8
;     for (int n = 0; n < 32; ++n) {
;       float* p = Ubuf + (((size_t)bh * 32 + n) * 64 + d) * 128 + v4 * 4;
;       const f32x4 u = *(const f32x4*)p;
;       const float e = Ebuf[((size_t)bh * 32 + n) * 64 + d];
;       *(f32x4*)p = S;
;       S = e * (S + u);
;     }
;   }
.LBB0_877:
	s_or_b64 exec, exec, s[0:1]
	v_mov_b32_e32 v0, v190
	v_readlane_b32 s0, v253, 3
	s_waitcnt lgkmcnt(0)
	s_barrier
	s_nop 0
	v_add_u32_e32 v2, s0, v0
	s_mov_b32 s0, 0x10000
	v_cmp_gt_i32_e32 vcc, s0, v2
	s_and_saveexec_b64 s[0:1], vcc
	s_mov_b64 s[6:7], 0x40000
	s_cbranch_execz .LBB0_880
	v_ashrrev_i32_e32 v4, 11, v2
	v_ashrrev_i32_e32 v5, 31, v4
	v_bfe_u32 v2, v2, 5, 6
	v_lshlrev_b64 v[6:7], 13, v[4:5]
	v_and_b32_e32 v0, 31, v0
	v_lshl_or_b32 v6, v2, 2, v6
	v_lshlrev_b64 v[8:9], 20, v[4:5]
	v_lshlrev_b32_e32 v2, 9, v2
	v_lshlrev_b32_e32 v0, 4, v0
	v_or3_b32 v8, v8, v2, v0
	v_mov_b32_e32 v2, 0
	s_mov_b32 s2, 32
	v_mov_b32_e32 v3, v2
	v_mov_b32_e32 v4, v2
	v_mov_b32_e32 v5, v2
	s_add_u32 s4, s90, 0x25920000
	s_addc_u32 s5, s91, 0
	global_load_dword v62, v6, s[4:5] offset:0
	global_load_dword v63, v6, s[4:5] offset:256
	global_load_dword v64, v6, s[4:5] offset:512
	global_load_dword v65, v6, s[4:5] offset:768
	global_load_dword v66, v6, s[4:5] offset:1024
	global_load_dword v67, v6, s[4:5] offset:1280
	global_load_dword v68, v6, s[4:5] offset:1536
	global_load_dword v69, v6, s[4:5] offset:1792
	global_load_dword v70, v6, s[4:5] offset:2048
	global_load_dword v71, v6, s[4:5] offset:2304
	global_load_dword v72, v6, s[4:5] offset:2560
	global_load_dword v73, v6, s[4:5] offset:2816
	global_load_dword v74, v6, s[4:5] offset:3072
	global_load_dword v75, v6, s[4:5] offset:3328
	global_load_dword v76, v6, s[4:5] offset:3584
	global_load_dword v77, v6, s[4:5] offset:3840
	s_add_u32 s4, s90, 0x25921000
	s_addc_u32 s5, s91, 0
	global_load_dword v78, v6, s[4:5] offset:0
	global_load_dword v79, v6, s[4:5] offset:256
	global_load_dword v80, v6, s[4:5] offset:512
	global_load_dword v81, v6, s[4:5] offset:768
	global_load_dword v82, v6, s[4:5] offset:1024
	global_load_dword v83, v6, s[4:5] offset:1280
	global_load_dword v84, v6, s[4:5] offset:1536
	global_load_dword v85, v6, s[4:5] offset:1792
	global_load_dword v86, v6, s[4:5] offset:2048
	global_load_dword v87, v6, s[4:5] offset:2304
	global_load_dword v88, v6, s[4:5] offset:2560
	global_load_dword v89, v6, s[4:5] offset:2816
	global_load_dword v90, v6, s[4:5] offset:3072
	global_load_dword v91, v6, s[4:5] offset:3328
	global_load_dword v92, v6, s[4:5] offset:3584
	s_add_u32 s2, s90, 0x23120000
	s_addc_u32 s3, s91, 0
	global_load_dwordx4 v[108:111], v8, s[2:3]
	s_add_u32 s2, s90, 0x23128000
	s_addc_u32 s3, s91, 0
	global_load_dwordx4 v[112:115], v8, s[2:3]
	s_add_u32 s2, s90, 0x23130000
	s_addc_u32 s3, s91, 0
	global_load_dwordx4 v[116:119], v8, s[2:3]
	s_add_u32 s2, s90, 0x23138000
	s_addc_u32 s3, s91, 0
	global_load_dwordx4 v[120:123], v8, s[2:3]
	s_add_u32 s2, s90, 0x23140000
	s_addc_u32 s3, s91, 0
	global_load_dwordx4 v[124:127], v8, s[2:3]
	s_add_u32 s2, s90, 0x23148000
	s_addc_u32 s3, s91, 0
	global_load_dwordx4 v[128:131], v8, s[2:3]
	s_add_u32 s2, s90, 0x23150000
	s_addc_u32 s3, s91, 0
	global_load_dwordx4 v[132:135], v8, s[2:3]
	s_add_u32 s2, s90, 0x23158000
	s_addc_u32 s3, s91, 0
	global_load_dwordx4 v[136:139], v8, s[2:3]
	s_add_u32 s2, s90, 0x23160000
	s_addc_u32 s3, s91, 0
	global_load_dwordx4 v[140:143], v8, s[2:3]
	s_add_u32 s2, s90, 0x23168000
	s_addc_u32 s3, s91, 0
	global_load_dwordx4 v[172:175], v8, s[2:3]
	s_add_u32 s2, s90, 0x23170000
	s_addc_u32 s3, s91, 0
	global_load_dwordx4 v[176:179], v8, s[2:3]
	s_add_u32 s2, s90, 0x23178000
	s_addc_u32 s3, s91, 0
	global_load_dwordx4 v[180:183], v8, s[2:3]
	s_add_u32 s2, s90, 0x23180000
	s_addc_u32 s3, s91, 0
	global_load_dwordx4 v[184:187], v8, s[2:3]
	s_add_u32 s2, s90, 0x23188000
	s_addc_u32 s3, s91, 0
	global_load_dwordx4 v[208:211], v8, s[2:3]
	s_add_u32 s2, s90, 0x23190000
	s_addc_u32 s3, s91, 0
	global_load_dwordx4 v[212:215], v8, s[2:3]
	s_add_u32 s2, s90, 0x23198000
	s_addc_u32 s3, s91, 0
	global_load_dwordx4 v[220:223], v8, s[2:3]
	s_add_u32 s2, s90, 0x231a0000
	s_addc_u32 s3, s91, 0
	global_load_dwordx4 v[224:227], v8, s[2:3]
	s_add_u32 s2, s90, 0x231a8000
	s_addc_u32 s3, s91, 0
	global_load_dwordx4 v[232:235], v8, s[2:3]
	s_add_u32 s2, s90, 0x231b0000
	s_addc_u32 s3, s91, 0
	global_load_dwordx4 v[236:239], v8, s[2:3]
	s_add_u32 s2, s90, 0x231b8000
	s_addc_u32 s3, s91, 0
	global_load_dwordx4 v[240:243], v8, s[2:3]
	s_add_u32 s2, s90, 0x231c0000
	s_addc_u32 s3, s91, 0
	global_load_dwordx4 v[152:155], v8, s[2:3]
	s_add_u32 s2, s90, 0x231c8000
	s_addc_u32 s3, s91, 0
	global_load_dwordx4 v[156:159], v8, s[2:3]
	s_add_u32 s2, s90, 0x231d0000
	s_addc_u32 s3, s91, 0
	global_load_dwordx4 v[160:163], v8, s[2:3]
	s_add_u32 s2, s90, 0x231d8000
	s_addc_u32 s3, s91, 0
	global_load_dwordx4 v[98:101], v8, s[2:3]
	s_add_u32 s2, s90, 0x231e0000
	s_addc_u32 s3, s91, 0
	global_load_dwordx4 v[102:105], v8, s[2:3]
	s_add_u32 s2, s90, 0x231e8000
	s_addc_u32 s3, s91, 0
	global_load_dwordx4 v[10:13], v8, s[2:3]
	s_add_u32 s2, s90, 0x231f0000
	s_addc_u32 s3, s91, 0
	global_load_dwordx4 v[14:17], v8, s[2:3]
	v_mov_b32_e32 v18, 0
	v_mov_b32_e32 v19, 0
	v_mov_b32_e32 v20, 0
	v_mov_b32_e32 v21, 0
	s_add_u32 s2, s90, 0x23120000
	s_addc_u32 s3, s91, 0
	global_store_dwordx4 v8, v[18:21], s[2:3]
	s_waitcnt vmcnt(27)
	v_add_f32_e32 v2, v18, v108
	v_add_f32_e32 v3, v19, v109
	v_add_f32_e32 v4, v20, v110
	v_add_f32_e32 v5, v21, v111
	s_nop 0
	s_add_u32 s2, s90, 0x231f8000
	s_addc_u32 s3, s91, 0
	global_load_dwordx4 v[108:111], v8, s[2:3]
	s_waitcnt vmcnt(59)
	v_mul_f32_e32 v18, v2, v62
	v_mul_f32_e32 v19, v3, v62
	v_mul_f32_e32 v20, v4, v62
	v_mul_f32_e32 v21, v5, v62
	s_add_u32 s2, s90, 0x23128000
	s_addc_u32 s3, s91, 0
	global_store_dwordx4 v8, v[18:21], s[2:3]
	s_waitcnt vmcnt(28)
; DI void gla_pass2(float* __restrict__ Ubuf, const float* __restrict__ Ebuf) {
;     ...
;     for (int n = 0; n < 32; ++n) {
;       float* p = Ubuf + (((size_t)bh * 32 + n) * 64 + d) * 128 + v4 * 4;
;       const f32x4 u = *(const f32x4*)p;
;       const float e = Ebuf[((size_t)bh * 32 + n) * 64 + d];
;       *(f32x4*)p = S;
;       S = e * (S + u);
;     }
	v_fma_f32 v2, v2, v62, v112
	v_fma_f32 v3, v3, v62, v113
	v_fma_f32 v4, v4, v62, v114
	v_fma_f32 v5, v5, v62, v115
	s_nop 0
	s_add_u32 s2, s90, 0x23200000
	s_addc_u32 s3, s91, 0
	global_load_dwordx4 v[112:115], v8, s[2:3]
	s_waitcnt vmcnt(60)
	v_mul_f32_e32 v18, v2, v63
	v_mul_f32_e32 v19, v3, v63
	v_mul_f32_e32 v20, v4, v63
	v_mul_f32_e32 v21, v5, v63
	s_add_u32 s2, s90, 0x23130000
	s_addc_u32 s3, s91, 0
	global_store_dwordx4 v8, v[18:21], s[2:3]
	s_waitcnt vmcnt(29)
	v_fma_f32 v2, v2, v63, v116
	v_fma_f32 v3, v3, v63, v117
	v_fma_f32 v4, v4, v63, v118
	v_fma_f32 v5, v5, v63, v119
	s_nop 0
	s_add_u32 s2, s90, 0x23208000
	s_addc_u32 s3, s91, 0
	global_load_dwordx4 v[116:119], v8, s[2:3]
	s_waitcnt vmcnt(61)
	v_mul_f32_e32 v18, v2, v64
	v_mul_f32_e32 v19, v3, v64
	v_mul_f32_e32 v20, v4, v64
	v_mul_f32_e32 v21, v5, v64
	s_add_u32 s2, s90, 0x23138000
	s_addc_u32 s3, s91, 0
	global_store_dwordx4 v8, v[18:21], s[2:3]
	s_waitcnt vmcnt(30)
	v_fma_f32 v2, v2, v64, v120
	v_fma_f32 v3, v3, v64, v121
	v_fma_f32 v4, v4, v64, v122
	v_fma_f32 v5, v5, v64, v123
	s_nop 0
	s_add_u32 s2, s90, 0x23210000
	s_addc_u32 s3, s91, 0
	global_load_dwordx4 v[120:123], v8, s[2:3]
	s_waitcnt vmcnt(62)
	v_mul_f32_e32 v18, v2, v65
	v_mul_f32_e32 v19, v3, v65
	v_mul_f32_e32 v20, v4, v65
	v_mul_f32_e32 v21, v5, v65
	s_add_u32 s2, s90, 0x23140000
	s_addc_u32 s3, s91, 0
	global_store_dwordx4 v8, v[18:21], s[2:3]
	s_waitcnt vmcnt(31)
	v_fma_f32 v2, v2, v65, v124
	v_fma_f32 v3, v3, v65, v125
	v_fma_f32 v4, v4, v65, v126
	v_fma_f32 v5, v5, v65, v127
	s_waitcnt vmcnt(62)
	v_mul_f32_e32 v18, v2, v66
	v_mul_f32_e32 v19, v3, v66
	v_mul_f32_e32 v20, v4, v66
	v_mul_f32_e32 v21, v5, v66
	s_add_u32 s2, s90, 0x23148000
	s_addc_u32 s3, s91, 0
	global_store_dwordx4 v8, v[18:21], s[2:3]
	s_waitcnt vmcnt(31)
	v_fma_f32 v2, v2, v66, v128
	v_fma_f32 v3, v3, v66, v129
	v_fma_f32 v4, v4, v66, v130
	v_fma_f32 v5, v5, v66, v131
	s_waitcnt vmcnt(62)
	v_mul_f32_e32 v18, v2, v67
	v_mul_f32_e32 v19, v3, v67
	v_mul_f32_e32 v20, v4, v67
	v_mul_f32_e32 v21, v5, v67
	s_add_u32 s2, s90, 0x23150000
	s_addc_u32 s3, s91, 0
	global_store_dwordx4 v8, v[18:21], s[2:3]
	s_waitcnt vmcnt(31)
	v_fma_f32 v2, v2, v67, v132
	v_fma_f32 v3, v3, v67, v133
	v_fma_f32 v4, v4, v67, v134
	v_fma_f32 v5, v5, v67, v135
	s_waitcnt vmcnt(62)
	v_mul_f32_e32 v18, v2, v68
	v_mul_f32_e32 v19, v3, v68
	v_mul_f32_e32 v20, v4, v68
	v_mul_f32_e32 v21, v5, v68
	s_add_u32 s2, s90, 0x23158000
	s_addc_u32 s3, s91, 0
	global_store_dwordx4 v8, v[18:21], s[2:3]
	s_waitcnt vmcnt(31)
	v_fma_f32 v2, v2, v68, v136
	v_fma_f32 v3, v3, v68, v137
	v_fma_f32 v4, v4, v68, v138
	v_fma_f32 v5, v5, v68, v139
	s_waitcnt vmcnt(62)
	v_mul_f32_e32 v18, v2, v69
	v_mul_f32_e32 v19, v3, v69
	v_mul_f32_e32 v20, v4, v69
	v_mul_f32_e32 v21, v5, v69
	s_add_u32 s2, s90, 0x23160000
	s_addc_u32 s3, s91, 0
	global_store_dwordx4 v8, v[18:21], s[2:3]
	s_waitcnt vmcnt(31)
	v_add_f32_e32 v2, v18, v140
	v_add_f32_e32 v3, v19, v141
	v_add_f32_e32 v4, v20, v142
	v_add_f32_e32 v5, v21, v143
	s_waitcnt vmcnt(62)
	v_mul_f32_e32 v18, v2, v70
	v_mul_f32_e32 v19, v3, v70
	v_mul_f32_e32 v20, v4, v70
	v_mul_f32_e32 v21, v5, v70
	s_add_u32 s2, s90, 0x23168000
	s_addc_u32 s3, s91, 0
	global_store_dwordx4 v8, v[18:21], s[2:3]
	s_waitcnt vmcnt(31)
	v_fma_f32 v2, v2, v70, v172
	v_fma_f32 v3, v3, v70, v173
	v_fma_f32 v4, v4, v70, v174
	v_fma_f32 v5, v5, v70, v175
	s_waitcnt vmcnt(62)
	v_mul_f32_e32 v18, v2, v71
	v_mul_f32_e32 v19, v3, v71
	v_mul_f32_e32 v20, v4, v71
	v_mul_f32_e32 v21, v5, v71
	s_add_u32 s2, s90, 0x23170000
	s_addc_u32 s3, s91, 0
	global_store_dwordx4 v8, v[18:21], s[2:3]
	s_waitcnt vmcnt(31)
	v_fma_f32 v2, v2, v71, v176
	v_fma_f32 v3, v3, v71, v177
	v_fma_f32 v4, v4, v71, v178
	v_fma_f32 v5, v5, v71, v179
	s_waitcnt vmcnt(62)
	v_mul_f32_e32 v18, v2, v72
	v_mul_f32_e32 v19, v3, v72
	v_mul_f32_e32 v20, v4, v72
	v_mul_f32_e32 v21, v5, v72
	s_add_u32 s2, s90, 0x23178000
	s_addc_u32 s3, s91, 0
	global_store_dwordx4 v8, v[18:21], s[2:3]
	s_waitcnt vmcnt(31)
	v_fma_f32 v2, v2, v72, v180
	v_fma_f32 v3, v3, v72, v181
	v_fma_f32 v4, v4, v72, v182
	v_fma_f32 v5, v5, v72, v183
	s_waitcnt vmcnt(62)
	v_mul_f32_e32 v18, v2, v73
	v_mul_f32_e32 v19, v3, v73
	v_mul_f32_e32 v20, v4, v73
	v_mul_f32_e32 v21, v5, v73
	s_add_u32 s2, s90, 0x23180000
	s_addc_u32 s3, s91, 0
	global_store_dwordx4 v8, v[18:21], s[2:3]
	s_waitcnt vmcnt(31)
	v_fma_f32 v2, v2, v73, v184
	v_fma_f32 v3, v3, v73, v185
	v_fma_f32 v4, v4, v73, v186
	v_fma_f32 v5, v5, v73, v187
	s_waitcnt vmcnt(62)
	v_mul_f32_e32 v18, v2, v74
	v_mul_f32_e32 v19, v3, v74
	v_mul_f32_e32 v20, v4, v74
	v_mul_f32_e32 v21, v5, v74
	s_add_u32 s2, s90, 0x23188000
	s_addc_u32 s3, s91, 0
	global_store_dwordx4 v8, v[18:21], s[2:3]
	s_waitcnt vmcnt(31)
	v_fma_f32 v2, v2, v74, v208
	v_fma_f32 v3, v3, v74, v209
	v_fma_f32 v4, v4, v74, v210
	v_fma_f32 v5, v5, v74, v211
	s_waitcnt vmcnt(62)
	v_mul_f32_e32 v18, v2, v75
	v_mul_f32_e32 v19, v3, v75
	v_mul_f32_e32 v20, v4, v75
	v_mul_f32_e32 v21, v5, v75
	s_add_u32 s2, s90, 0x23190000
	s_addc_u32 s3, s91, 0
	global_store_dwordx4 v8, v[18:21], s[2:3]
	s_waitcnt vmcnt(31)
	v_fma_f32 v2, v2, v75, v212
	v_fma_f32 v3, v3, v75, v213
	v_fma_f32 v4, v4, v75, v214
	v_fma_f32 v5, v5, v75, v215
	s_waitcnt vmcnt(62)
	v_mul_f32_e32 v18, v2, v76
	v_mul_f32_e32 v19, v3, v76
	v_mul_f32_e32 v20, v4, v76
	v_mul_f32_e32 v21, v5, v76
	s_add_u32 s2, s90, 0x23198000
	s_addc_u32 s3, s91, 0
	global_store_dwordx4 v8, v[18:21], s[2:3]
	s_waitcnt vmcnt(31)
	v_fma_f32 v2, v2, v76, v220
	v_fma_f32 v3, v3, v76, v221
	v_fma_f32 v4, v4, v76, v222
	v_fma_f32 v5, v5, v76, v223
	s_waitcnt vmcnt(62)
; DI void gla_pass2(float* __restrict__ Ubuf, const float* __restrict__ Ebuf) {
;     ...
;     for (int n = 0; n < 32; ++n) {
;       float* p = Ubuf + (((size_t)bh * 32 + n) * 64 + d) * 128 + v4 * 4;
;       const f32x4 u = *(const f32x4*)p;
;       const float e = Ebuf[((size_t)bh * 32 + n) * 64 + d];
;       *(f32x4*)p = S;
;       S = e * (S + u);
;     }
	v_mul_f32_e32 v18, v2, v77
	v_mul_f32_e32 v19, v3, v77
	v_mul_f32_e32 v20, v4, v77
	v_mul_f32_e32 v21, v5, v77
	s_add_u32 s2, s90, 0x231a0000
	s_addc_u32 s3, s91, 0
	global_store_dwordx4 v8, v[18:21], s[2:3]
	s_waitcnt vmcnt(31)
	v_add_f32_e32 v2, v18, v224
	v_add_f32_e32 v3, v19, v225
	v_add_f32_e32 v4, v20, v226
	v_add_f32_e32 v5, v21, v227
	s_waitcnt vmcnt(62)
	v_mul_f32_e32 v18, v2, v78
	v_mul_f32_e32 v19, v3, v78
	v_mul_f32_e32 v20, v4, v78
	v_mul_f32_e32 v21, v5, v78
	s_add_u32 s2, s90, 0x231a8000
	s_addc_u32 s3, s91, 0
	global_store_dwordx4 v8, v[18:21], s[2:3]
	s_waitcnt vmcnt(31)
	v_fma_f32 v2, v2, v78, v232
	v_fma_f32 v3, v3, v78, v233
	v_fma_f32 v4, v4, v78, v234
	v_fma_f32 v5, v5, v78, v235
	s_waitcnt vmcnt(62)
	v_mul_f32_e32 v18, v2, v79
	v_mul_f32_e32 v19, v3, v79
	v_mul_f32_e32 v20, v4, v79
	v_mul_f32_e32 v21, v5, v79
	s_add_u32 s2, s90, 0x231b0000
	s_addc_u32 s3, s91, 0
	global_store_dwordx4 v8, v[18:21], s[2:3]
	s_waitcnt vmcnt(31)
	v_fma_f32 v2, v2, v79, v236
	v_fma_f32 v3, v3, v79, v237
	v_fma_f32 v4, v4, v79, v238
	v_fma_f32 v5, v5, v79, v239
	s_waitcnt vmcnt(62)
	v_mul_f32_e32 v18, v2, v80
	v_mul_f32_e32 v19, v3, v80
	v_mul_f32_e32 v20, v4, v80
	v_mul_f32_e32 v21, v5, v80
	s_add_u32 s2, s90, 0x231b8000
	s_addc_u32 s3, s91, 0
	global_store_dwordx4 v8, v[18:21], s[2:3]
	s_waitcnt vmcnt(31)
	v_fma_f32 v2, v2, v80, v240
	v_fma_f32 v3, v3, v80, v241
	v_fma_f32 v4, v4, v80, v242
	v_fma_f32 v5, v5, v80, v243
	s_waitcnt vmcnt(62)
	v_mul_f32_e32 v18, v2, v81
	v_mul_f32_e32 v19, v3, v81
	v_mul_f32_e32 v20, v4, v81
	v_mul_f32_e32 v21, v5, v81
	s_add_u32 s2, s90, 0x231c0000
	s_addc_u32 s3, s91, 0
	global_store_dwordx4 v8, v[18:21], s[2:3]
	s_waitcnt vmcnt(31)
	v_fma_f32 v2, v2, v81, v152
	v_fma_f32 v3, v3, v81, v153
	v_fma_f32 v4, v4, v81, v154
	v_fma_f32 v5, v5, v81, v155
	s_waitcnt vmcnt(62)
	v_mul_f32_e32 v18, v2, v82
	v_mul_f32_e32 v19, v3, v82
	v_mul_f32_e32 v20, v4, v82
	v_mul_f32_e32 v21, v5, v82
	s_add_u32 s2, s90, 0x231c8000
	s_addc_u32 s3, s91, 0
	global_store_dwordx4 v8, v[18:21], s[2:3]
	s_waitcnt vmcnt(31)
	v_fma_f32 v2, v2, v82, v156
	v_fma_f32 v3, v3, v82, v157
	v_fma_f32 v4, v4, v82, v158
	v_fma_f32 v5, v5, v82, v159
	s_waitcnt vmcnt(62)
	v_mul_f32_e32 v18, v2, v83
	v_mul_f32_e32 v19, v3, v83
	v_mul_f32_e32 v20, v4, v83
	v_mul_f32_e32 v21, v5, v83
	s_add_u32 s2, s90, 0x231d0000
	s_addc_u32 s3, s91, 0
	global_store_dwordx4 v8, v[18:21], s[2:3]
	s_waitcnt vmcnt(31)
	v_fma_f32 v2, v2, v83, v160
	v_fma_f32 v3, v3, v83, v161
	v_fma_f32 v4, v4, v83, v162
	v_fma_f32 v5, v5, v83, v163
	s_waitcnt vmcnt(62)
	v_mul_f32_e32 v18, v2, v84
	v_mul_f32_e32 v19, v3, v84
	v_mul_f32_e32 v20, v4, v84
	v_mul_f32_e32 v21, v5, v84
	s_add_u32 s2, s90, 0x231d8000
	s_addc_u32 s3, s91, 0
	global_store_dwordx4 v8, v[18:21], s[2:3]
	s_waitcnt vmcnt(31)
	v_fma_f32 v2, v2, v84, v98
	v_fma_f32 v3, v3, v84, v99
	v_fma_f32 v4, v4, v84, v100
	v_fma_f32 v5, v5, v84, v101
	s_waitcnt vmcnt(62)
	v_mul_f32_e32 v18, v2, v85
	v_mul_f32_e32 v19, v3, v85
	v_mul_f32_e32 v20, v4, v85
	v_mul_f32_e32 v21, v5, v85
	s_add_u32 s2, s90, 0x231e0000
	s_addc_u32 s3, s91, 0
	global_store_dwordx4 v8, v[18:21], s[2:3]
	s_waitcnt vmcnt(31)
	v_add_f32_e32 v2, v18, v102
	v_add_f32_e32 v3, v19, v103
	v_add_f32_e32 v4, v20, v104
	v_add_f32_e32 v5, v21, v105
	s_waitcnt vmcnt(62)
	v_mul_f32_e32 v18, v2, v86
	v_mul_f32_e32 v19, v3, v86
	v_mul_f32_e32 v20, v4, v86
	v_mul_f32_e32 v21, v5, v86
	s_add_u32 s2, s90, 0x231e8000
	s_addc_u32 s3, s91, 0
	global_store_dwordx4 v8, v[18:21], s[2:3]
	s_waitcnt vmcnt(31)
	v_fma_f32 v2, v2, v86, v10
	v_fma_f32 v3, v3, v86, v11
	v_fma_f32 v4, v4, v86, v12
	v_fma_f32 v5, v5, v86, v13
	s_waitcnt vmcnt(62)
	v_mul_f32_e32 v18, v2, v87
	v_mul_f32_e32 v19, v3, v87
	v_mul_f32_e32 v20, v4, v87
	v_mul_f32_e32 v21, v5, v87
	s_add_u32 s2, s90, 0x231f0000
	s_addc_u32 s3, s91, 0
	global_store_dwordx4 v8, v[18:21], s[2:3]
	s_waitcnt vmcnt(31)
	v_fma_f32 v2, v2, v87, v14
	v_fma_f32 v3, v3, v87, v15
	v_fma_f32 v4, v4, v87, v16
	v_fma_f32 v5, v5, v87, v17
	s_waitcnt vmcnt(62)
	v_mul_f32_e32 v18, v2, v88
	v_mul_f32_e32 v19, v3, v88
	v_mul_f32_e32 v20, v4, v88
	v_mul_f32_e32 v21, v5, v88
	s_add_u32 s2, s90, 0x231f8000
	s_addc_u32 s3, s91, 0
	global_store_dwordx4 v8, v[18:21], s[2:3]
	s_waitcnt vmcnt(30)
	v_fma_f32 v2, v2, v88, v108
	v_fma_f32 v3, v3, v88, v109
	v_fma_f32 v4, v4, v88, v110
	v_fma_f32 v5, v5, v88, v111
	s_waitcnt vmcnt(62)
	v_mul_f32_e32 v18, v2, v89
	v_mul_f32_e32 v19, v3, v89
	v_mul_f32_e32 v20, v4, v89
	v_mul_f32_e32 v21, v5, v89
	s_add_u32 s2, s90, 0x23200000
	s_addc_u32 s3, s91, 0
	global_store_dwordx4 v8, v[18:21], s[2:3]
	s_waitcnt vmcnt(29)
	v_fma_f32 v2, v2, v89, v112
	v_fma_f32 v3, v3, v89, v113
	v_fma_f32 v4, v4, v89, v114
	v_fma_f32 v5, v5, v89, v115
	s_waitcnt vmcnt(62)
	v_mul_f32_e32 v18, v2, v90
	v_mul_f32_e32 v19, v3, v90
	v_mul_f32_e32 v20, v4, v90
	v_mul_f32_e32 v21, v5, v90
	s_add_u32 s2, s90, 0x23208000
	s_addc_u32 s3, s91, 0
	global_store_dwordx4 v8, v[18:21], s[2:3]
	s_waitcnt vmcnt(28)
	v_fma_f32 v2, v2, v90, v116
	v_fma_f32 v3, v3, v90, v117
	v_fma_f32 v4, v4, v90, v118
	v_fma_f32 v5, v5, v90, v119
	s_waitcnt vmcnt(62)
	v_mul_f32_e32 v18, v2, v91
	v_mul_f32_e32 v19, v3, v91
	v_mul_f32_e32 v20, v4, v91
	v_mul_f32_e32 v21, v5, v91
	s_add_u32 s2, s90, 0x23210000
	s_addc_u32 s3, s91, 0
	global_store_dwordx4 v8, v[18:21], s[2:3]
	s_waitcnt vmcnt(27)
	v_fma_f32 v2, v2, v91, v120
	v_fma_f32 v3, v3, v91, v121
	v_fma_f32 v4, v4, v91, v122
	v_fma_f32 v5, v5, v91, v123
	s_waitcnt vmcnt(62)
	v_mul_f32_e32 v18, v2, v92
	v_mul_f32_e32 v19, v3, v92
	v_mul_f32_e32 v20, v4, v92
	v_mul_f32_e32 v21, v5, v92
	s_add_u32 s2, s90, 0x23218000
	s_addc_u32 s3, s91, 0
	global_store_dwordx4 v8, v[18:21], s[2:3]
